# ff fix-up phase loop: the U-edge row load is issued together with the conv-edge row load at the top of each iteration instead of after the conditional neighbour loads
# speedup vs baseline: 1.0028x; 1.0028x over previous
; __global__ void __launch_bounds__(512) mega(Params p) {
;     ...
;                 for (int i = bx * 512 + tid; i < nblk * 2 * (DFF / 4); i += G * 512) {
;                     const int c = (i % (DFF / 4)) * 4, be = i / (DFF / 4), blk = be >> 1, e = be & 1; const int r = blk * 64 + (e ? 63 : 0);
;                     f32x4 conv = *(const f32x4*)(PE + (size_t)be * DFF + c);
;                     if (e == 0) { const bool start = r < TLAT ? ((r & (SEQ - 1)) == 0) : (((r - TLAT) & (CTXL - 1)) == 0);
;                         if (!start) conv += *(const f32x4*)(cw + c) * *(const f32x4*)(GE + ((size_t)(blk - 1) * 2 + 1) * DFF + c); }
;                     else { const int r1 = r + 1; const bool end = r1 < TLAT ? ((r1 & (SEQ - 1)) == 0) : (((r1 - TLAT) & (CTXL - 1)) == 0);
;                         if (!end) conv += *(const f32x4*)(cw + 2 * DFF + c) * *(const f32x4*)(GE + ((size_t)(blk + 1) * 2) * DFF + c); }
;                     const f32x4 uu = *(const f32x4*)(UE + (size_t)be * DFF + c);
;                     v2u w; w.x = pk2(conv.x * __builtin_amdgcn_rcpf(1.f + __expf(-conv.x)) * uu.x, conv.y * __builtin_amdgcn_rcpf(1.f + __expf(-conv.y)) * uu.y);
;                     w.y = pk2(conv.z * __builtin_amdgcn_rcpf(1.f + __expf(-conv.z)) * uu.z, conv.w * __builtin_amdgcn_rcpf(1.f + __expf(-conv.w)) * uu.w);
;                     *(v2u*)(HID + (size_t)r * DFF + c) = w;
.LBB0_26:
	s_or_b64 exec, exec, s[20:21]
	s_waitcnt vmcnt(0)
	v_mul_f32_e32 v10, 0xbfb8aa3b, v0
	v_mul_f32_e32 v11, 0xbfb8aa3b, v1
	v_exp_f32_e32 v10, v10
	v_exp_f32_e32 v11, v11
	v_readlane_b32 s2, v254, 16
	v_readlane_b32 s3, v254, 17
	v_add_f32_e32 v10, 1.0, v10
	v_add_f32_e32 v11, 1.0, v11
	v_rcp_f32_e32 v10, v10
	v_rcp_f32_e32 v11, v11
	v_add_u32_e32 v12, s58, v12
	v_cmp_le_i32_e32 vcc, s0, v12
	v_add_u32_e32 v13, s1, v13
	v_pk_mul_f32 v[0:1], v[0:1], v[10:11]
	s_or_b64 s[16:17], vcc, s[16:17]
	s_waitcnt vmcnt(0)
	v_pk_mul_f32 v[0:1], v[22:23], v[0:1]
	s_nop 0
	v_cvt_pk_bf16_f32 v0, v0, v1
	v_mul_f32_e32 v1, 0xbfb8aa3b, v2
	v_exp_f32_e32 v1, v1
	s_nop 0
	v_add_f32_e32 v1, 1.0, v1
	v_rcp_f32_e32 v6, v1
	v_mul_f32_e32 v1, 0xbfb8aa3b, v3
	v_exp_f32_e32 v1, v1
	s_nop 0
	v_add_f32_e32 v1, 1.0, v1
	v_rcp_f32_e32 v7, v1
	s_nop 0
	v_pk_mul_f32 v[2:3], v[2:3], v[6:7]
	s_nop 0
	v_pk_mul_f32 v[2:3], v[24:25], v[2:3]
	s_nop 0
	v_cvt_pk_bf16_f32 v1, v2, v3
	v_mov_b64_e32 v[2:3], s[2:3]
	s_movk_i32 s2, 0x1600
	v_mad_i64_i32 v[2:3], s[2:3], v14, s2, v[2:3]
	v_lshl_add_u64 v[2:3], v[4:5], 1, v[2:3]
	global_store_dwordx2 v[2:3], v[0:1], off
	s_andn2_b64 exec, exec, s[16:17]
	s_cbranch_execz .LBB0_38
.LBB0_27:
	s_mov_b32 s2, 0x2e8ba2e9
	v_mul_hi_i32 v0, v12, s2
	v_lshrrev_b32_e32 v1, 31, v0
	v_ashrrev_i32_e32 v0, 7, v0
	v_add_u32_e32 v0, v0, v1
	v_mul_i32_i24_e32 v1, 0x2c0, v0
	v_lshlrev_b32_e32 v1, 2, v1
	v_ashrrev_i32_e32 v15, 1, v0
	v_sub_u32_e32 v4, v13, v1
	v_bfe_i32 v1, v0, 0, 1
	v_lshlrev_b32_e32 v2, 6, v15
	v_mul_hi_i32_i24_e32 v7, 0xb00, v0
	v_mul_i32_i24_e32 v6, 0xb00, v0
	v_and_b32_e32 v3, 1, v0
	v_and_or_b32 v14, v1, 63, v2
	v_lshl_add_u64 v[0:1], v[6:7], 2, s[10:11]
	v_ashrrev_i32_e32 v5, 31, v4
	v_lshl_add_u64 v[0:1], v[4:5], 2, v[0:1]
	v_cmp_eq_u32_e32 vcc, 1, v3
	global_load_dwordx4 v[0:3], v[0:1], off
	v_lshl_add_u64 v[26:27], v[6:7], 2, s[12:13]
	v_lshl_add_u64 v[26:27], v[4:5], 2, v[26:27]
	global_load_dwordx4 v[22:25], v[26:27], off
	s_mov_b64 s[18:19], 0
	s_and_saveexec_b64 s[2:3], vcc
	s_xor_b64 s[20:21], exec, s[2:3]
	s_cbranch_execz .LBB0_32
	v_and_b32_e32 v8, 0x1fff, v14
	s_movk_i32 s2, 0x1fff
	v_cmp_eq_u32_e32 vcc, s2, v8
	s_movk_i32 s2, 0xff
	v_cmp_eq_u32_sdwa s[2:3], v14, s2 src0_sel:BYTE_0 src1_sel:DWORD
	v_cndmask_b32_e64 v8, 0, 1, vcc
	v_cmp_gt_i32_e32 vcc, s70, v14
	v_cndmask_b32_e64 v9, 0, 1, s[2:3]
	s_nop 0
	v_cndmask_b32_e32 v8, v9, v8, vcc
	v_and_b32_e32 v8, 1, v8
	v_cmp_eq_u32_e32 vcc, 1, v8
	s_xor_b64 s[2:3], vcc, -1
	s_and_saveexec_b64 s[22:23], s[2:3]
	s_xor_b64 s[22:23], exec, s[22:23]
	s_cbranch_execz .LBB0_30
	v_add_u32_e32 v8, 1, v15
	v_readlane_b32 s2, v254, 22
	v_mul_hi_i32_i24_e32 v9, 0x5800, v8
	v_mul_i32_i24_e32 v8, 0x5800, v8
	v_readlane_b32 s3, v254, 23
	s_mov_b64 s[18:19], exec
	s_nop 0
	v_lshl_add_u64 v[8:9], s[2:3], 0, v[8:9]
